# mixer chunk loop: ALiBi band scores via float relative position + per-tile clamp bounds instead of per-element integer index/mask math (-80 instr per chunk)
# speedup vs baseline: 1.2166x; 1.0049x over previous
; #define LAS __attribute__((address_space(3)))
; template <int DH, bool SOFTMAX, bool PREFETCH, class Spec>
; __device__ __forceinline__ void wave_attn(const Spec& sp, int nch, LAS bf16* vl, int lane, f32x4 (&oacc)[DH / 16], float& m_run, float& l_run) {
;     ...
;         for (int c = 0; c < nch; ++c) {
;             bf16x8 kf[2][KS];
; #pragma unroll
;             for (int kt = 0; kt < 2; ++kt)
; #pragma unroll
;                 for (int ks = 0; ks < KS; ++ks) kf[kt][ks] = kn[kt][ks];
; #pragma unroll
;             for (int r = 0; r < NP; ++r) { const int p = lane + 64 * r, key = p / PPR, pc = p % PPR; *(LAS v4u*)(vl + key * P + pc * 8) = vn[r]; }
;             if (c + 1 < nch) WA_LOAD(c + 1);
;             f32x4 st[2];
; #pragma unroll
;             for (int kt = 0; kt < 2; ++kt) { st[kt] = (f32x4){0.f, 0.f, 0.f, 0.f};
; #pragma unroll
;                 for (int ks = 0; ks < KS; ++ks) st[kt] = __builtin_amdgcn_mfma_f32_16x16x32_bf16(kf[kt][ks], qf[ks], st[kt], 0, 0, 0); }
;             float pv[8];
; #pragma unroll
;             for (int kt = 0; kt < 2; ++kt)
; #pragma unroll
;                 for (int j = 0; j < 4; ++j) pv[kt * 4 + j] = sp.score(st[kt][j], i, 32 * c + 16 * kt + 4 * g + j);
.LBB0_322:
	s_or_b32 s8, s10, s33
	s_lshr_b32 s9, s8, s16
	s_and_b32 s8, s8, s17
	s_lshl_b32 s8, s8, 4
	s_add_i32 s18, s9, s13
	s_lshl_b32 s8, s8, s2
	s_add_i32 s18, s18, s8
	v_add_u32_e32 v155, s18, v126
	v_lshrrev_b32_e32 v197, s2, v155
	v_mov_b32_e32 v195, 0x7ff
	v_sub_u32_e32 v194, 0, v197
	v_lshrrev_b32_e32 v195, s2, v195
	v_max_i32_e32 v194, 0xffffffc0, v194
	v_sub_u32_e32 v195, v195, v197
	v_cvt_f32_i32_e32 v194, v194
	v_min_i32_e32 v195, 64, v195
	v_ldexp_f32 v196, v71, s2
	v_cvt_f32_i32_e32 v195, v195
	v_mul_f32_e32 v196, 0xbfb8aa3b, v196
	v_mad_i64_i32 v[0:1], s[8:9], v155, s90, v[72:73]
	global_load_dwordx4 v[16:19], v[0:1], off
	global_load_dwordx4 v[20:23], v[0:1], off offset:64
	v_add_u32_e32 v0, s18, v127
	v_med3_i32 v0, v0, 0, v187
	v_mul_u32_u24_e32 v136, 0x1c00, v0
	v_lshl_add_u64 v[0:1], v[74:75], 0, v[136:137]
	global_load_dwordx4 v[28:31], v[0:1], off
	global_load_dwordx4 v[24:27], v[0:1], off offset:64
	v_add_u32_e32 v0, s18, v128
	v_med3_i32 v0, v0, 0, v187
	v_mul_u32_u24_e32 v136, 0x1c00, v0
	v_lshl_add_u64 v[0:1], v[74:75], 0, v[136:137]
	global_load_dwordx4 v[36:39], v[0:1], off
	global_load_dwordx4 v[32:35], v[0:1], off offset:64
	v_add_u32_e32 v0, s18, v129
	v_med3_i32 v0, v0, 0, v187
	v_add_u32_e32 v2, s18, v130
	v_mul_u32_u24_e32 v136, 0x1c00, v0
	v_med3_i32 v2, v2, 0, v187
	v_lshl_add_u64 v[0:1], v[76:77], 0, v[136:137]
	v_mul_u32_u24_e32 v136, 0x1c00, v2
	v_lshl_add_u64 v[2:3], v[78:79], 0, v[136:137]
	global_load_dwordx4 v[40:43], v[0:1], off
	global_load_dwordx4 v[44:47], v[2:3], off
	v_add_u32_e32 v0, s18, v131
	v_med3_i32 v0, v0, 0, v187
	v_add_u32_e32 v2, s18, v132
	v_mul_u32_u24_e32 v136, 0x1c00, v0
	v_med3_i32 v2, v2, 0, v187
	v_lshl_add_u64 v[0:1], v[80:81], 0, v[136:137]
	v_mul_u32_u24_e32 v136, 0x1c00, v2
	v_lshl_add_u64 v[2:3], v[82:83], 0, v[136:137]
	global_load_dwordx4 v[48:51], v[0:1], off
	global_load_dwordx4 v[52:55], v[2:3], off
	v_mov_b32_e32 v70, 0
	s_xor_b64 s[8:9], s[0:1], -1
	s_mov_b32 s10, 0
	v_mov_b32_e32 v136, 0xf149f2ca
	v_mov_b32_e32 v0, 0
	v_mov_b32_e32 v1, v70
	v_mov_b32_e32 v2, v70
	v_mov_b32_e32 v3, v70
	v_mov_b32_e32 v4, 0
	v_mov_b32_e32 v5, v70
	v_mov_b32_e32 v6, v70
	v_mov_b32_e32 v7, v70
	v_mov_b32_e32 v8, 0
	v_mov_b32_e32 v9, v70
	v_mov_b32_e32 v10, v70
	v_mov_b32_e32 v11, v70
	v_mov_b32_e32 v12, 0
	v_mov_b32_e32 v13, v70
	v_mov_b32_e32 v14, v70
	v_mov_b32_e32 v15, v70
.LBB0_323:
	s_waitcnt vmcnt(4)
	v_mov_b64_e32 v[170:171], v[34:35]
	v_mov_b64_e32 v[162:163], v[26:27]
	v_mov_b64_e32 v[168:169], v[32:33]
	v_add_u32_e32 v32, s10, v88
	v_mov_b64_e32 v[160:161], v[24:25]
	v_subrev_u32_e32 v24, 32, v32
	v_mov_b64_e32 v[158:159], v[30:31]
	v_lshlrev_b32_e32 v24, s2, v24
	v_mov_b64_e32 v[156:157], v[28:29]
	s_waitcnt vmcnt(3)
	ds_write_b128 v122, v[40:43]
	s_waitcnt vmcnt(2)
	ds_write_b128 v123, v[44:47]
	s_waitcnt vmcnt(1)
	ds_write_b128 v124, v[48:51]
	s_waitcnt vmcnt(0)
	ds_write_b128 v125, v[52:55]
	v_add_u32_e32 v24, s18, v24
	v_add_lshl_u32 v32, v32, -16, s2
	v_add_u32_e32 v40, s10, v121
	v_med3_i32 v24, v24, 0, v187
	v_add_u32_e32 v32, s18, v32
	v_lshlrev_b32_e32 v40, s2, v40
	v_add_u32_e32 v44, s10, v120
	v_mov_b32_e32 v173, v136
	v_mul_u32_u24_e32 v136, 0x1c00, v24
	v_med3_i32 v32, v32, 0, v187
	v_add_u32_e32 v40, s18, v40
	v_lshlrev_b32_e32 v44, s2, v44
	v_add_u32_e32 v48, s10, v119
	v_mov_b64_e32 v[166:167], v[38:39]
	v_lshl_add_u64 v[24:25], v[74:75], 0, v[136:137]
	v_mul_u32_u24_e32 v136, 0x1c00, v32
	v_med3_i32 v40, v40, 0, v187
	v_add_u32_e32 v44, s18, v44
	v_lshlrev_b32_e32 v48, s2, v48
	v_add_u32_e32 v52, s10, v118
	v_mov_b64_e32 v[164:165], v[36:37]
	v_lshl_add_u64 v[32:33], v[74:75], 0, v[136:137]
	v_mul_u32_u24_e32 v136, 0x1c00, v40
	v_med3_i32 v44, v44, 0, v187
	v_add_u32_e32 v48, s18, v48
	v_lshlrev_b32_e32 v52, s2, v52
	v_lshl_add_u64 v[40:41], v[76:77], 0, v[136:137]
	v_mul_u32_u24_e32 v136, 0x1c00, v44
	v_med3_i32 v48, v48, 0, v187
	v_add_u32_e32 v52, s18, v52
	v_mfma_f32_16x16x32_bf16 v[156:159], v[156:159], v[16:19], 0
	v_lshl_add_u64 v[44:45], v[78:79], 0, v[136:137]
	v_mul_u32_u24_e32 v136, 0x1c00, v48
	v_med3_i32 v52, v52, 0, v187
	v_lshl_add_u64 v[48:49], v[80:81], 0, v[136:137]
	v_mul_u32_u24_e32 v136, 0x1c00, v52
	v_lshl_add_u64 v[52:53], v[82:83], 0, v[136:137]
	v_mov_b32_e32 v172, v70
	v_mfma_f32_16x16x32_bf16 v[156:159], v[160:163], v[20:23], v[156:159]
	v_mfma_f32_16x16x32_bf16 v[160:163], v[164:167], v[16:19], 0
	v_mfma_f32_16x16x32_bf16 v[160:163], v[168:171], v[20:23], v[160:163]
	v_add_u32_e32 v166, s10, v117
	global_load_dwordx4 v[28:31], v[24:25], off
	s_nop 0
	global_load_dwordx4 v[24:27], v[24:25], off offset:64
	global_load_dwordx4 v[36:39], v[32:33], off
	s_nop 0
	global_load_dwordx4 v[32:35], v[32:33], off offset:64
	global_load_dwordx4 v[40:43], v[40:41], off
	global_load_dwordx4 v[44:47], v[44:45], off
	global_load_dwordx4 v[48:51], v[48:49], off
	v_cvt_f32_i32_e32 v190, v166
	v_add_f32_e32 v200, 0xc2800000, v190
	v_add_f32_e32 v201, 0xc27c0000, v190
	v_add_f32_e32 v202, 0xc2780000, v190
	v_add_f32_e32 v203, 0xc2740000, v190
	v_add_f32_e32 v204, 0xc2400000, v190
	v_add_f32_e32 v205, 0xc23c0000, v190
	v_add_f32_e32 v206, 0xc2380000, v190
	v_add_f32_e32 v207, 0xc2340000, v190
	v_med3_f32 v208, v200, v194, v195
	v_med3_f32 v209, v201, v194, v195
	v_med3_f32 v210, v202, v194, v195
	v_med3_f32 v211, v203, v194, v195
	v_med3_f32 v212, v204, v194, v195
	v_med3_f32 v213, v205, v194, v195
	v_med3_f32 v214, v206, v194, v195
	v_med3_f32 v215, v207, v194, v195
	v_mul_f32_e32 v216, 0x3e38aa3b, v156
	v_mul_f32_e32 v217, 0x3e38aa3b, v157
	v_mul_f32_e32 v218, 0x3e38aa3b, v158
	v_mul_f32_e32 v219, 0x3e38aa3b, v159
	v_mul_f32_e32 v220, 0x3e38aa3b, v160
	v_mul_f32_e32 v221, 0x3e38aa3b, v161
	v_mul_f32_e32 v222, 0x3e38aa3b, v162
	v_mul_f32_e32 v223, 0x3e38aa3b, v163
	v_fma_f32 v216, |v200|, v196, v216
	v_fma_f32 v217, |v201|, v196, v217
	v_fma_f32 v218, |v202|, v196, v218
	v_fma_f32 v219, |v203|, v196, v219
	v_fma_f32 v220, |v204|, v196, v220
	v_fma_f32 v221, |v205|, v196, v221
	v_fma_f32 v222, |v206|, v196, v222
	v_fma_f32 v223, |v207|, v196, v223
	v_cmp_eq_f32_e64 vcc, v208, v200
	v_cmp_eq_f32_e64 s[0:1], v209, v201
	s_nop 0
	v_cndmask_b32_e64 v164, v188, v216, vcc
	v_cmp_eq_f32_e64 vcc, v210, v202
	v_cndmask_b32_e64 v165, v188, v217, s[0:1]
	v_cmp_eq_f32_e64 s[0:1], v211, v203
	v_cndmask_b32_e64 v158, v188, v218, vcc
	v_cmp_eq_f32_e64 vcc, v212, v204
	v_cndmask_b32_e64 v159, v188, v219, s[0:1]
	v_cmp_eq_f32_e64 s[0:1], v213, v205
	v_cndmask_b32_e64 v160, v188, v220, vcc
	v_cmp_eq_f32_e64 vcc, v214, v206
	v_cndmask_b32_e64 v161, v188, v221, s[0:1]
	v_cmp_eq_f32_e64 s[0:1], v215, v207
	v_cndmask_b32_e64 v162, v188, v222, vcc
	v_max_f32_e32 v136, v164, v165
	v_cndmask_b32_e64 v70, v188, v223, s[0:1]
	v_max3_f32 v136, v136, v158, v159
	v_max3_f32 v136, v136, v160, v161
	v_max3_f32 v136, v136, v162, v70
	ds_bpermute_b32 v141, v96, v136
	global_load_dwordx4 v[52:55], v[52:53], off
	s_add_i32 s10, s10, 32
	s_cmpk_lg_i32 s10, 0x80
	s_waitcnt lgkmcnt(0)
; __device__ __forceinline__ unsigned pk2(float lo, float hi) { return f2bf(lo) | (f2bf(hi) << 16); }
; template <int DH, bool SOFTMAX, bool PREFETCH, class Spec>
; __device__ __forceinline__ void wave_attn(const Spec& sp, int nch, LAS bf16* vl, int lane, f32x4 (&oacc)[DH / 16], float& m_run, float& l_run) {
;     ...
;             if constexpr (SOFTMAX) {
;                 float cm = pv[0];
; #pragma unroll
;                 for (int r = 1; r < 8; ++r) cm = fmaxf(cm, pv[r]);
;                 cm = fmaxf(cm, __shfl_xor(cm, 16)); cm = fmaxf(cm, __shfl_xor(cm, 32));
;                 const float mn = fmaxf(m_run, cm), sc = exp2f(m_run - mn);
;                 float ls = 0.f;
; #pragma unroll
;                 for (int r = 0; r < 8; ++r) { pv[r] = exp2f(pv[r] - mn); ls += pv[r]; }
;                 ls += __shfl_xor(ls, 16); ls += __shfl_xor(ls, 32);
;                 l_run = l_run * sc + ls; m_run = mn;
; #pragma unroll
;                 for (int dt = 0; dt < DT; ++dt) oacc[dt] = oacc[dt] * sc;
;             }
;             bf16x8 pb; { v4u t; t.x = pk2(pv[0], pv[1]); t.y = pk2(pv[2], pv[3]); t.z = pk2(pv[4], pv[5]); t.w = pk2(pv[6], pv[7]); pb = __builtin_bit_cast(bf16x8, t); }
;             if constexpr (USE_TR) {
; #pragma unroll
;                 for (int d4 = 0; d4 < DT; d4 += 4) { bf16x8 vf4[4]; read_vfrags4_trp<P>(vl + 16 * d4, i, g, vf4);
; #pragma unroll
;                     for (int dt = 0; dt < 4; ++dt) oacc[d4 + dt] = __builtin_amdgcn_mfma_f32_16x16x32_bf16(vf4[dt], pb, oacc[d4 + dt], 0, 0, 0); }
	v_max_f32_e32 v141, v141, v141
	v_max_f32_e32 v136, v136, v141
	ds_bpermute_b32 v141, v97, v136
	s_waitcnt lgkmcnt(0)
	v_max3_f32 v136, v173, v136, v141
	v_sub_f32_e32 v156, v164, v136
	v_sub_f32_e32 v158, v158, v136
	v_sub_f32_e32 v159, v159, v136
	v_exp_f32_e32 v156, v156
	v_sub_f32_e32 v160, v160, v136
	v_sub_f32_e32 v161, v161, v136
	v_mov_b32_e32 v157, v156
	v_sub_f32_e32 v156, v165, v136
	v_sub_f32_e32 v162, v162, v136
	v_sub_f32_e32 v70, v70, v136
	v_exp_f32_e32 v156, v156
	v_sub_f32_e32 v141, v173, v136
	v_exp_f32_e32 v158, v158
	v_mov_b32_e32 v163, v156
	v_exp_f32_e32 v159, v159
	v_add_f32_e32 v156, v157, v163
	v_exp_f32_e32 v160, v160
	v_add_f32_e32 v156, v158, v156
	v_exp_f32_e32 v161, v161
	v_add_f32_e32 v156, v159, v156
	v_exp_f32_e32 v162, v162
	v_add_f32_e32 v156, v160, v156
	v_exp_f32_e32 v70, v70
	v_add_f32_e32 v156, v161, v156
	v_add_f32_e32 v156, v162, v156
	v_mov_b32_e32 v164, v70
	v_add_f32_e32 v70, v164, v156
	v_bfe_u32 v165, v159, 16, 1
	v_exp_f32_e32 v141, v141
	v_bfe_u32 v166, v163, 16, 1
	v_add3_u32 v165, v159, v165, s86
	v_mov_b32_e32 v156, v141
	ds_bpermute_b32 v141, v96, v70
	v_pk_mul_f32 v[2:3], v[2:3], v[156:157] op_sel_hi:[1,0]
	v_pk_mul_f32 v[0:1], v[0:1], v[156:157] op_sel_hi:[1,0]
	v_pk_mul_f32 v[6:7], v[6:7], v[156:157] op_sel_hi:[1,0]
	v_pk_mul_f32 v[4:5], v[4:5], v[156:157] op_sel_hi:[1,0]
	s_waitcnt lgkmcnt(0)
	v_add_f32_e32 v70, v70, v141
	ds_bpermute_b32 v141, v97, v70
	v_pk_mul_f32 v[10:11], v[10:11], v[156:157] op_sel_hi:[1,0]
	v_pk_mul_f32 v[8:9], v[8:9], v[156:157] op_sel_hi:[1,0]
	v_pk_mul_f32 v[14:15], v[14:15], v[156:157] op_sel_hi:[1,0]
	v_pk_mul_f32 v[12:13], v[12:13], v[156:157] op_sel_hi:[1,0]
	s_waitcnt lgkmcnt(0)
	v_add_f32_e32 v70, v70, v141
	v_fmac_f32_e32 v70, v172, v156
	v_bfe_u32 v141, v164, 16, 1
	v_bfe_u32 v156, v161, 16, 1
	v_add3_u32 v156, v161, v156, s86
	v_add3_u32 v141, v164, v141, s86
	v_bfe_u32 v159, v157, 16, 1
	v_bfe_u32 v161, v158, 16, 1
	v_bfe_u32 v164, v160, 16, 1
	v_add3_u32 v163, v163, v166, s86
	v_bfe_u32 v166, v162, 16, 1
	v_add3_u32 v160, v160, v164, s86
	v_add3_u32 v158, v158, v161, s86
	v_add3_u32 v157, v157, v159, s86
	v_add3_u32 v162, v162, v166, s86
	v_lshrrev_b32_e32 v161, 16, v157
	v_lshrrev_b32_e32 v157, 16, v158
	v_lshrrev_b32_e32 v158, 16, v160
	v_lshrrev_b32_e32 v159, 16, v162
	v_and_or_b32 v158, v156, s85, v158
	v_and_or_b32 v157, v165, s85, v157
	v_and_or_b32 v156, v163, s85, v161
	ds_read_b64_tr_b16 v[172:173], v98
	ds_read_b64_tr_b16 v[168:169], v98 offset:32
	ds_read_b64_tr_b16 v[164:165], v98 offset:64
	ds_read_b64_tr_b16 v[160:161], v98 offset:96
	ds_read_b64_tr_b16 v[174:175], v99
	ds_read_b64_tr_b16 v[170:171], v99 offset:32
	ds_read_b64_tr_b16 v[166:167], v99 offset:64
	ds_read_b64_tr_b16 v[162:163], v99 offset:96
	s_waitcnt lgkmcnt(0)
	v_and_or_b32 v159, v141, s85, v159
	v_bfi_b32 v174, s87, v174, v174
	v_bfi_b32 v170, s87, v170, v170
	v_bfi_b32 v166, s87, v166, v166
	v_bfi_b32 v162, s87, v162, v162
	v_mfma_f32_16x16x32_bf16 v[0:3], v[172:175], v[156:159], v[0:3]
	v_mfma_f32_16x16x32_bf16 v[4:7], v[168:171], v[156:159], v[4:7]
	v_mfma_f32_16x16x32_bf16 v[8:11], v[164:167], v[156:159], v[8:11]
	v_mfma_f32_16x16x32_bf16 v[12:15], v[160:163], v[156:159], v[12:15]
	s_cbranch_scc1 .LBB0_323
	s_waitcnt vmcnt(7)
	v_mfma_f32_16x16x32_bf16 v[28:31], v[28:31], v[16:19], 0
	s_waitcnt vmcnt(3)
	ds_write_b128 v122, v[40:43]
	s_waitcnt vmcnt(2)
	ds_write_b128 v123, v[44:47]
	s_waitcnt vmcnt(1)
	ds_write_b128 v124, v[48:51]
	s_waitcnt vmcnt(0)
	ds_write_b128 v125, v[52:55]
	s_movk_i32 s0, 0x110
	v_mfma_f32_16x16x32_bf16 v[16:19], v[36:39], v[16:19], 0
	v_mfma_f32_16x16x32_bf16 v[24:27], v[24:27], v[20:23], v[28:31]
	v_mfma_f32_16x16x32_bf16 v[16:19], v[32:35], v[20:23], v[16:19]
	v_add_u32_e32 v20, s18, v133
	v_cmp_gt_u32_e32 vcc, s84, v20
	s_nop 4
	v_fma_f32 v20, v24, s76, -v134
	s_and_b64 vcc, s[38:39], vcc
	v_mul_f32_e32 v20, 0x3fb8aa3b, v20
	v_cndmask_b32_e32 v21, v188, v20, vcc
	v_add_u32_e32 v20, s18, v135
	v_cmp_gt_u32_e32 vcc, s84, v20
	v_fma_f32 v20, v25, s76, -v139
	s_and_b64 vcc, s[40:41], vcc
	v_mul_f32_e32 v20, 0x3fb8aa3b, v20
	v_cndmask_b32_e32 v22, v188, v20, vcc
	v_add_u32_e32 v20, s18, v142
	v_cmp_gt_u32_e32 vcc, s84, v20
	v_fma_f32 v20, v26, s76, -v143
	s_and_b64 vcc, s[42:43], vcc
	v_mul_f32_e32 v20, 0x3fb8aa3b, v20
	v_cndmask_b32_e32 v23, v188, v20, vcc
	v_add_u32_e32 v20, s18, v144
	v_cmp_gt_u32_e32 vcc, s84, v20
	v_fma_f32 v20, v27, s76, -v145
	s_and_b64 vcc, s[44:45], vcc
	v_mul_f32_e32 v20, 0x3fb8aa3b, v20
	v_cndmask_b32_e32 v24, v188, v20, vcc
	v_add_u32_e32 v20, s18, v146
	v_cmp_gt_u32_e32 vcc, s84, v20
	v_fma_f32 v16, v16, s76, -v147
	s_and_b64 vcc, s[46:47], vcc
	v_mul_f32_e32 v16, 0x3fb8aa3b, v16
	v_add_u32_e32 v20, s18, v148
	v_cndmask_b32_e32 v16, v188, v16, vcc
	v_cmp_gt_u32_e32 vcc, s84, v20
	v_fma_f32 v17, v17, s76, -v149
	s_and_b64 vcc, s[48:49], vcc
	v_mul_f32_e32 v17, 0x3fb8aa3b, v17
	v_add_u32_e32 v20, s18, v150
	v_cndmask_b32_e32 v17, v188, v17, vcc
	v_cmp_gt_u32_e32 vcc, s84, v20
	v_fma_f32 v18, v18, s76, -v151
	s_and_b64 vcc, s[50:51], vcc
	v_mul_f32_e32 v18, 0x3fb8aa3b, v18
	v_add_u32_e32 v20, s18, v152
	v_cndmask_b32_e32 v18, v188, v18, vcc
	v_cmp_gt_u32_e32 vcc, s84, v20
	v_fma_f32 v19, v19, s76, -v153
	v_max_f32_e32 v20, v21, v22
	s_and_b64 vcc, s[52:53], vcc
	v_mul_f32_e32 v19, 0x3fb8aa3b, v19
	v_max3_f32 v20, v20, v23, v24
	v_cndmask_b32_e32 v19, v188, v19, vcc
	v_max3_f32 v20, v20, v16, v17
	v_max3_f32 v20, v20, v18, v19
	ds_bpermute_b32 v25, v96, v20
	s_waitcnt lgkmcnt(0)
; #define LAS __attribute__((address_space(3)))
; __device__ __forceinline__ unsigned pk2(float lo, float hi) { return f2bf(lo) | (f2bf(hi) << 16); }
; template <int DH, bool SOFTMAX, bool PREFETCH, class Spec>
; __device__ __forceinline__ void wave_attn(const Spec& sp, int nch, LAS bf16* vl, int lane, f32x4 (&oacc)[DH / 16], float& m_run, float& l_run) {
;     ...
;             if constexpr (SOFTMAX) {
;                 float cm = pv[0];
; #pragma unroll
;                 for (int r = 1; r < 8; ++r) cm = fmaxf(cm, pv[r]);
;                 cm = fmaxf(cm, __shfl_xor(cm, 16)); cm = fmaxf(cm, __shfl_xor(cm, 32));
;                 const float mn = fmaxf(m_run, cm), sc = exp2f(m_run - mn);
;                 float ls = 0.f;
; #pragma unroll
;                 for (int r = 0; r < 8; ++r) { pv[r] = exp2f(pv[r] - mn); ls += pv[r]; }
;                 ls += __shfl_xor(ls, 16); ls += __shfl_xor(ls, 32);
;                 l_run = l_run * sc + ls; m_run = mn;
; #pragma unroll
;                 for (int dt = 0; dt < DT; ++dt) oacc[dt] = oacc[dt] * sc;
;             }
;             bf16x8 pb; { v4u t; t.x = pk2(pv[0], pv[1]); t.y = pk2(pv[2], pv[3]); t.z = pk2(pv[4], pv[5]); t.w = pk2(pv[6], pv[7]); pb = __builtin_bit_cast(bf16x8, t); }
;             if constexpr (USE_TR) {
; #pragma unroll
;                 for (int d4 = 0; d4 < DT; d4 += 4) { bf16x8 vf4[4]; read_vfrags4_trp<P>(vl + 16 * d4, i, g, vf4);
; #pragma unroll
;                     for (int dt = 0; dt < 4; ++dt) oacc[d4 + dt] = __builtin_amdgcn_mfma_f32_16x16x32_bf16(vf4[dt], pb, oacc[d4 + dt], 0, 0, 0); }
; __device__ __forceinline__ void mixer_phase(const Ctx& C, const bf16* PROJ, bf16* MIX, const float* decay_logit  , const float* ret_gain, const float* att_gain) {
;     ...
;                 const int row = tb + i * d - T0;
;                 LAS float* orow = OL + row * 68 + 4 * g;
;                 if (pat > 0) {
;                     const float m0 = ML[row * 2], l0 = ML[row * 2 + 1];
;                     const float mn = fmaxf(m0, m), a = exp2f(m0 - mn), bb = exp2f(m - mn);
; #pragma unroll
;                     for (int dt = 0; dt < 4; ++dt) { const f32x4 p0 = *(LAS f32x4*)(orow + 16 * dt); o[dt] = p0 * a + o[dt] * bb; }
;                     l = l0 * a + l * bb; m = mn;
	v_max_f32_e32 v25, v25, v25
	v_max_f32_e32 v20, v20, v25
	ds_bpermute_b32 v25, v97, v20
	s_waitcnt lgkmcnt(0)
	v_max3_f32 v20, v136, v20, v25
	v_sub_f32_e32 v21, v21, v20
	v_sub_f32_e32 v23, v23, v20
	v_sub_f32_e32 v24, v24, v20
	v_exp_f32_e32 v21, v21
	v_sub_f32_e32 v16, v16, v20
	v_sub_f32_e32 v17, v17, v20
	v_mov_b32_e32 v26, v21
	v_sub_f32_e32 v21, v22, v20
	v_sub_f32_e32 v18, v18, v20
	v_sub_f32_e32 v19, v19, v20
	v_exp_f32_e32 v21, v21
	v_sub_f32_e32 v25, v136, v20
	v_exp_f32_e32 v23, v23
	v_mov_b32_e32 v22, v21
	v_exp_f32_e32 v24, v24
	v_add_f32_e32 v21, v26, v22
	v_exp_f32_e32 v16, v16
	v_add_f32_e32 v21, v23, v21
	v_add_f32_e32 v21, v24, v21
	v_mov_b32_e32 v27, v16
	v_add_f32_e32 v16, v27, v21
	v_bfe_u32 v28, v24, 16, 1
	v_exp_f32_e32 v17, v17
	v_bfe_u32 v29, v22, 16, 1
	v_exp_f32_e32 v18, v18
	v_add_f32_e32 v16, v17, v16
	v_exp_f32_e32 v19, v19
	v_add_f32_e32 v16, v18, v16
	v_add_f32_e32 v21, v19, v16
	v_mov_b32_e32 v16, v25
	v_exp_f32_e32 v16, v16
	v_add3_u32 v22, v22, v29, s86
	v_add3_u32 v24, v24, v28, s86
	ds_bpermute_b32 v25, v96, v21
	v_pk_mul_f32 v[2:3], v[2:3], v[16:17] op_sel_hi:[1,0]
	v_pk_mul_f32 v[0:1], v[0:1], v[16:17] op_sel_hi:[1,0]
	v_pk_mul_f32 v[6:7], v[6:7], v[16:17] op_sel_hi:[1,0]
	v_pk_mul_f32 v[4:5], v[4:5], v[16:17] op_sel_hi:[1,0]
	s_waitcnt lgkmcnt(0)
	v_add_f32_e32 v21, v21, v25
	ds_bpermute_b32 v25, v97, v21
	v_pk_mul_f32 v[10:11], v[10:11], v[16:17] op_sel_hi:[1,0]
	v_pk_mul_f32 v[8:9], v[8:9], v[16:17] op_sel_hi:[1,0]
	v_pk_mul_f32 v[14:15], v[14:15], v[16:17] op_sel_hi:[1,0]
	v_pk_mul_f32 v[12:13], v[12:13], v[16:17] op_sel_hi:[1,0]
	s_waitcnt lgkmcnt(0)
	v_add_f32_e32 v21, v21, v25
	v_fmac_f32_e32 v21, v70, v16
	v_bfe_u32 v16, v19, 16, 1
	v_bfe_u32 v25, v17, 16, 1
	v_add3_u32 v17, v17, v25, s86
	v_add3_u32 v16, v19, v16, s86
	v_bfe_u32 v19, v26, 16, 1
	v_bfe_u32 v25, v23, 16, 1
	v_bfe_u32 v28, v27, 16, 1
	v_bfe_u32 v29, v18, 16, 1
	v_add3_u32 v18, v18, v29, s86
	v_add3_u32 v27, v27, v28, s86
	v_add3_u32 v23, v23, v25, s86
	v_add3_u32 v19, v26, v19, s86
	v_lshrrev_b32_e32 v25, 16, v19
	v_lshrrev_b32_e32 v23, 16, v23
	v_lshrrev_b32_e32 v26, 16, v27
	v_lshrrev_b32_e32 v18, 16, v18
	v_and_or_b32 v19, v16, s85, v18
	v_and_or_b32 v18, v17, s85, v26
	v_and_or_b32 v17, v24, s85, v23
	v_and_or_b32 v16, v22, s85, v25
	ds_read_b64_tr_b16 v[34:35], v98
	ds_read_b64_tr_b16 v[30:31], v98 offset:32
	ds_read_b64_tr_b16 v[26:27], v98 offset:64
	ds_read_b64_tr_b16 v[22:23], v98 offset:96
	ds_read_b64_tr_b16 v[36:37], v99
	ds_read_b64_tr_b16 v[32:33], v99 offset:32
	ds_read_b64_tr_b16 v[28:29], v99 offset:64
	ds_read_b64_tr_b16 v[24:25], v99 offset:96
	s_waitcnt lgkmcnt(0)
	s_andn2_b64 vcc, exec, s[4:5]
	v_bfi_b32 v36, s87, v36, v36
	v_bfi_b32 v32, s87, v32, v32
	v_bfi_b32 v28, s87, v28, v28
	v_bfi_b32 v24, s87, v24, v24
	v_mfma_f32_16x16x32_bf16 v[0:3], v[34:37], v[16:19], v[0:3]
	v_mfma_f32_16x16x32_bf16 v[4:7], v[30:33], v[16:19], v[4:7]
	v_mfma_f32_16x16x32_bf16 v[8:11], v[26:29], v[16:19], v[8:11]
	v_subrev_u32_e32 v29, s13, v155
	v_mfma_f32_16x16x32_bf16 v[12:15], v[22:25], v[16:19], v[12:15]
	v_mul_lo_u32 v16, v29, s0
	v_add_u32_e32 v42, v116, v16
	s_cbranch_vccnz .LBB0_327
	v_lshl_add_u32 v16, v29, 3, 0
	v_add_u32_e32 v16, 0x1a000, v16
	ds_read_b64 v[18:19], v16
	ds_read_b128 v[22:25], v42 offset:36864
	v_max_f32_e32 v17, v20, v20
	s_waitcnt lgkmcnt(1)
	v_max_f32_e32 v16, v18, v18
	v_max_f32_e32 v16, v16, v17
	v_sub_f32_e32 v17, v18, v16
	s_nop 1
	v_exp_f32_e32 v17, v17
	s_nop 0
	v_mov_b32_e32 v18, v17
	v_sub_f32_e32 v17, v20, v16
	s_waitcnt lgkmcnt(0)
	v_pk_mul_f32 v[22:23], v[22:23], v[18:19] op_sel_hi:[1,0]
	v_pk_mul_f32 v[24:25], v[24:25], v[18:19] op_sel_hi:[1,0]
	v_exp_f32_e32 v17, v17
	s_and_b64 vcc, exec, s[6:7]
	v_mov_b32_e32 v26, v17
	v_pk_fma_f32 v[2:3], v[2:3], v[26:27], v[24:25] op_sel_hi:[1,0,1]
	v_pk_fma_f32 v[0:1], v[0:1], v[26:27], v[22:23] op_sel_hi:[1,0,1]
	ds_read_b128 v[22:25], v42 offset:36928
	v_mov_b32_e32 v20, v19
	s_waitcnt lgkmcnt(0)
	v_pk_mul_f32 v[22:23], v[22:23], v[18:19] op_sel_hi:[1,0]
	v_pk_mul_f32 v[24:25], v[24:25], v[18:19] op_sel_hi:[1,0]
	v_pk_fma_f32 v[4:5], v[4:5], v[26:27], v[22:23] op_sel_hi:[1,0,1]
	v_pk_fma_f32 v[6:7], v[6:7], v[26:27], v[24:25] op_sel_hi:[1,0,1]
	ds_read_b128 v[22:25], v42 offset:36992
	s_waitcnt lgkmcnt(0)
	v_pk_mul_f32 v[22:23], v[18:19], v[22:23] op_sel_hi:[0,1]
	v_pk_mul_f32 v[24:25], v[18:19], v[24:25] op_sel_hi:[0,1]
	v_pk_fma_f32 v[10:11], v[10:11], v[26:27], v[24:25] op_sel_hi:[1,0,1]
	v_pk_fma_f32 v[8:9], v[8:9], v[26:27], v[22:23] op_sel_hi:[1,0,1]
	ds_read_b128 v[22:25], v42 offset:37056
	s_waitcnt lgkmcnt(0)
	v_pk_mul_f32 v[22:23], v[18:19], v[22:23] op_sel_hi:[0,1]
	v_pk_mul_f32 v[24:25], v[18:19], v[24:25] op_sel_hi:[0,1]
	v_pk_fma_f32 v[12:13], v[12:13], v[26:27], v[22:23] op_sel_hi:[1,0,1]
	v_mov_b32_e32 v19, v26
	v_mul_f32_e32 v22, v21, v26
	v_pk_fma_f32 v[14:15], v[14:15], v[26:27], v[24:25] op_sel_hi:[1,0,1]
	v_pk_fma_f32 v[18:19], v[20:21], v[18:19], v[22:23] op_sel_hi:[1,1,0]
	s_cbranch_vccz .LBB0_328
	v_mov_b32_e32 v17, v18
	s_mov_b64 s[10:11], -1
	v_mov_b64_e32 v[20:21], v[16:17]
	s_cbranch_execz .LBB0_329
	s_branch .LBB0_330
